# up GEMM K-loop: LDS-DMA addresses as SGPR base + 32-bit VGPR offset (drops 16 64-bit VALU adds per iteration)
# speedup vs baseline: 1.0097x; 1.0097x over previous
; #define PG8_STAGE(bufoff, gbase, voff) do { _Pragma("unroll") for (int _i = 0; _i < 2; ++_i) \
;         __builtin_amdgcn_global_load_lds((const unsigned*)((const char*)(gbase) + (voff)[_i]), (PG8_LAS unsigned*)(lds + (bufoff) + ldsw + _i * 8192), 16, 0, 0); } while (0)
; #define PG8_LDA(dst, b, h) do { _Pragma("unroll") for (int m = 0; m < 4; ++m) _Pragma("unroll") for (int k = 0; k < 2; ++k) dst[m][k] = *(const PG8_LAS bf16x8*)(lds + PG8_SA(b, h) + aoff + m * 2048 + k * 1024); } while (0)
; #define PG8_LDB(dst, b, h) do { _Pragma("unroll") for (int n = 0; n < 2; ++n) _Pragma("unroll") for (int k = 0; k < 2; ++k) dst[n][k] = *(const PG8_LAS bf16x8*)(lds + PG8_SB(b, h) + boff + n * 2048 + k * 1024); } while (0)
; #define PG8_MMA(ai, bj, At, Bt) do { __builtin_amdgcn_s_setprio(1); _Pragma("unroll") for (int m = 0; m < 4; ++m) _Pragma("unroll") for (int n = 0; n < 2; ++n) _Pragma("unroll") for (int k = 0; k < 2; ++k) \
;         acc[ai][bj][m][n] = __builtin_amdgcn_mfma_f32_16x16x32_bf16(Bt[n][k], At[m][k], acc[ai][bj][m][n], 0, 0, 0); __builtin_amdgcn_s_setprio(0); } while (0)
; #define PG8_WAIT_V(n) asm volatile("s_waitcnt vmcnt(" #n ")" ::: "memory")
; #define PG8_WAIT_L(n) asm volatile("s_waitcnt lgkmcnt(" #n ")" ::: "memory")
; template <class Epi, class Sched, bool ALIGN_EPI = true>
; __device__ __forceinline__ void gemm_phase(PG8_LAS unsigned char* lds, const Gemm g, const Sched& S, const Epi& E, const int tid) {
;     ...
;         for (int t = 0; t < nt; t += 2) {
;             const bool last = (t == nt - 2);
;             const char* a1 = cA + (size_t)(t + 1) * kstep;
;             const char* a2 = last ? nA : cA + (size_t)(t + 2) * kstep; const char* b2 = last ? nB : cB + (size_t)(t + 2) * kstep;
;             const char* a3 = a2 + kstep; const char* b3 = b2 + kstep;
;             if (last && has_next) S.a_ready(nxt);
;             PG8_LDB(B0, 0, 0); PG8_LDB(B1, 0, 1); PG8_SCHED; PG8_LDA(At, 0, 0); PG8_STAGE(PG8_SA(1, 1), a1 + hstepA, voffA);
;             PG8_WAIT_V(8); PG8_WAIT_L(0); PG8_BAR; PG8_MMA(0, 0, At, B0); PG8_MMA(0, 1, At, B1); PG8_BAR; PG8_SCHED;
;             PG8_LDA(At, 0, 1); PG8_STAGE(PG8_SB(0, 0), b2, voffB); PG8_STAGE(PG8_SB(0, 1), b2 + hstepB, voffB); PG8_STAGE(PG8_SA(0, 0), a2, voffA);
;             PG8_WAIT_V(8); PG8_WAIT_L(0); PG8_BAR; PG8_MMA(1, 0, At, B0); PG8_MMA(1, 1, At, B1); PG8_BAR; PG8_SCHED;
.LBB0_1238:
	s_add_u32 s15, s74, 0xfff80080
	s_addc_u32 s16, s75, -1
	s_add_i32 s17, 0, 0x10000
	s_cmp_eq_u32 s21, 28
	s_cselect_b32 s79, s8, s16
	s_cselect_b32 s78, s11, s15
	s_cselect_b32 s77, s13, s20
	s_cselect_b32 s76, s18, s19
	s_add_i32 s15, 0, 0x14000
	v_add_u32_e32 v88, s17, v193
	v_add_u32_e32 v104, s15, v193
	ds_read_b128 v[72:75], v88
	ds_read_b128 v[76:79], v88 offset:1024
	ds_read_b128 v[84:87], v88 offset:2048
	ds_read_b128 v[88:91], v88 offset:3072
	ds_read_b128 v[92:95], v104
	ds_read_b128 v[96:99], v104 offset:1024
	ds_read_b128 v[100:103], v104 offset:2048
	ds_read_b128 v[104:107], v104 offset:3072
	s_add_i32 m0, s86, 0xc000
	ds_read_b128 v[164:167], v200
	ds_read_b128 v[168:171], v200 offset:1024
	ds_read_b128 v[172:175], v200 offset:2048
	ds_read_b128 v[176:179], v200 offset:3072
	ds_read_b128 v[202:205], v200 offset:4096
	ds_read_b128 v[210:213], v200 offset:5120
	ds_read_b128 v[214:217], v200 offset:6144
	ds_read_b128 v[218:221], v200 offset:7168
	global_load_lds_dwordx4 v186, s[74:75]
	s_add_i32 m0, s86, 0xe000
	s_nop 0
	global_load_lds_dwordx4 v188, s[74:75]
	s_waitcnt vmcnt(8)
	s_waitcnt lgkmcnt(0)
	s_barrier
	s_waitcnt lgkmcnt(0)
	v_mfma_f32_16x16x32_bf16 v[160:163], v[72:75], v[164:167], v[160:163]
	v_mfma_f32_16x16x32_bf16 v[160:163], v[76:79], v[168:171], v[160:163]
	v_mfma_f32_16x16x32_bf16 v[156:159], v[84:87], v[164:167], v[156:159]
	v_mfma_f32_16x16x32_bf16 v[156:159], v[88:91], v[168:171], v[156:159]
	v_mfma_f32_16x16x32_bf16 v[144:147], v[72:75], v[172:175], v[144:147]
	v_mfma_f32_16x16x32_bf16 v[144:147], v[76:79], v[176:179], v[144:147]
	v_mfma_f32_16x16x32_bf16 v[140:143], v[84:87], v[172:175], v[140:143]
	v_mfma_f32_16x16x32_bf16 v[140:143], v[88:91], v[176:179], v[140:143]
	v_mfma_f32_16x16x32_bf16 v[128:131], v[72:75], v[202:205], v[128:131]
	v_mfma_f32_16x16x32_bf16 v[128:131], v[76:79], v[210:213], v[128:131]
	v_mfma_f32_16x16x32_bf16 v[124:127], v[84:87], v[202:205], v[124:127]
	v_mfma_f32_16x16x32_bf16 v[124:127], v[88:91], v[210:213], v[124:127]
	v_mfma_f32_16x16x32_bf16 v[80:83], v[72:75], v[214:217], v[80:83]
	v_mfma_f32_16x16x32_bf16 v[80:83], v[76:79], v[218:221], v[80:83]
	v_mfma_f32_16x16x32_bf16 v[68:71], v[84:87], v[214:217], v[68:71]
	v_mfma_f32_16x16x32_bf16 v[68:71], v[88:91], v[218:221], v[68:71]
	v_mfma_f32_16x16x32_bf16 v[152:155], v[92:95], v[164:167], v[152:155]
	v_mfma_f32_16x16x32_bf16 v[152:155], v[96:99], v[168:171], v[152:155]
	v_mfma_f32_16x16x32_bf16 v[148:151], v[100:103], v[164:167], v[148:151]
	v_mfma_f32_16x16x32_bf16 v[148:151], v[104:107], v[168:171], v[148:151]
	v_mfma_f32_16x16x32_bf16 v[136:139], v[92:95], v[172:175], v[136:139]
	v_mfma_f32_16x16x32_bf16 v[136:139], v[96:99], v[176:179], v[136:139]
	v_mfma_f32_16x16x32_bf16 v[132:135], v[100:103], v[172:175], v[132:135]
	v_mfma_f32_16x16x32_bf16 v[132:135], v[104:107], v[176:179], v[132:135]
	v_mfma_f32_16x16x32_bf16 v[120:123], v[92:95], v[202:205], v[120:123]
	v_mfma_f32_16x16x32_bf16 v[120:123], v[96:99], v[210:213], v[120:123]
	v_mfma_f32_16x16x32_bf16 v[116:119], v[100:103], v[202:205], v[116:119]
	v_mfma_f32_16x16x32_bf16 v[116:119], v[104:107], v[210:213], v[116:119]
	v_mfma_f32_16x16x32_bf16 v[112:115], v[92:95], v[214:217], v[112:115]
	v_mfma_f32_16x16x32_bf16 v[112:115], v[96:99], v[218:221], v[112:115]
	v_mfma_f32_16x16x32_bf16 v[108:111], v[100:103], v[214:217], v[108:111]
	v_mfma_f32_16x16x32_bf16 v[108:111], v[104:107], v[218:221], v[108:111]
	s_barrier
	s_add_i32 s16, s17, s85
	s_mov_b32 m0, s16
	ds_read_b128 v[164:167], v200 offset:16384
	ds_read_b128 v[168:171], v200 offset:17408
	ds_read_b128 v[172:175], v200 offset:18432
	ds_read_b128 v[176:179], v200 offset:19456
	ds_read_b128 v[202:205], v200 offset:20480
	ds_read_b128 v[210:213], v200 offset:21504
	ds_read_b128 v[214:217], v200 offset:22528
	ds_read_b128 v[218:221], v200 offset:23552
	global_load_lds_dwordx4 v2, s[76:77]
	s_add_i32 m0, s16, 0x2000
	s_add_u32 s96, s76, 0x80000
	s_addc_u32 s97, s77, 0
	s_add_i32 s15, s15, s85
	global_load_lds_dwordx4 v184, s[76:77]
	s_mov_b32 m0, s15
	s_nop 0
	global_load_lds_dwordx4 v2, s[96:97]
	s_add_i32 m0, s15, 0x2000
	s_nop 0
	global_load_lds_dwordx4 v184, s[96:97]
	s_mov_b32 m0, s86
	s_nop 0
	global_load_lds_dwordx4 v180, s[78:79]
	s_mov_b32 m0, s87
	s_nop 0
	global_load_lds_dwordx4 v182, s[78:79]
	s_waitcnt vmcnt(8)
	s_waitcnt lgkmcnt(0)
	s_barrier
	s_waitcnt lgkmcnt(0)
	v_mfma_f32_16x16x32_bf16 v[64:67], v[72:75], v[164:167], v[64:67]
	v_mfma_f32_16x16x32_bf16 v[64:67], v[76:79], v[168:171], v[64:67]
	v_mfma_f32_16x16x32_bf16 v[60:63], v[84:87], v[164:167], v[60:63]
	v_mfma_f32_16x16x32_bf16 v[60:63], v[88:91], v[168:171], v[60:63]
	v_mfma_f32_16x16x32_bf16 v[48:51], v[72:75], v[172:175], v[48:51]
	v_mfma_f32_16x16x32_bf16 v[48:51], v[76:79], v[176:179], v[48:51]
	v_mfma_f32_16x16x32_bf16 v[44:47], v[84:87], v[172:175], v[44:47]
	v_mfma_f32_16x16x32_bf16 v[44:47], v[88:91], v[176:179], v[44:47]
	v_mfma_f32_16x16x32_bf16 v[32:35], v[72:75], v[202:205], v[32:35]
	v_mfma_f32_16x16x32_bf16 v[32:35], v[76:79], v[210:213], v[32:35]
	v_mfma_f32_16x16x32_bf16 v[28:31], v[84:87], v[202:205], v[28:31]
	v_mfma_f32_16x16x32_bf16 v[28:31], v[88:91], v[210:213], v[28:31]
	v_mfma_f32_16x16x32_bf16 v[8:11], v[72:75], v[214:217], v[8:11]
	v_mfma_f32_16x16x32_bf16 v[8:11], v[76:79], v[218:221], v[8:11]
	v_mfma_f32_16x16x32_bf16 v[4:7], v[84:87], v[214:217], v[4:7]
	v_mfma_f32_16x16x32_bf16 v[4:7], v[88:91], v[218:221], v[4:7]
	v_mfma_f32_16x16x32_bf16 v[56:59], v[92:95], v[164:167], v[56:59]
	v_mfma_f32_16x16x32_bf16 v[56:59], v[96:99], v[168:171], v[56:59]
	v_mfma_f32_16x16x32_bf16 v[52:55], v[100:103], v[164:167], v[52:55]
	v_mfma_f32_16x16x32_bf16 v[52:55], v[104:107], v[168:171], v[52:55]
	v_mfma_f32_16x16x32_bf16 v[40:43], v[92:95], v[172:175], v[40:43]
	v_mfma_f32_16x16x32_bf16 v[40:43], v[96:99], v[176:179], v[40:43]
	v_mfma_f32_16x16x32_bf16 v[36:39], v[100:103], v[172:175], v[36:39]
	v_mfma_f32_16x16x32_bf16 v[36:39], v[104:107], v[176:179], v[36:39]
	v_mfma_f32_16x16x32_bf16 v[24:27], v[92:95], v[202:205], v[24:27]
	v_mfma_f32_16x16x32_bf16 v[24:27], v[96:99], v[210:213], v[24:27]
	v_mfma_f32_16x16x32_bf16 v[20:23], v[100:103], v[202:205], v[20:23]
	v_mfma_f32_16x16x32_bf16 v[20:23], v[104:107], v[210:213], v[20:23]
	v_mfma_f32_16x16x32_bf16 v[16:19], v[92:95], v[214:217], v[16:19]
	v_mfma_f32_16x16x32_bf16 v[16:19], v[96:99], v[218:221], v[16:19]
	v_mfma_f32_16x16x32_bf16 v[12:15], v[100:103], v[214:217], v[12:15]
	v_mfma_f32_16x16x32_bf16 v[12:15], v[104:107], v[218:221], v[12:15]
	s_barrier
; #define PG8_STAGE(bufoff, gbase, voff) do { _Pragma("unroll") for (int _i = 0; _i < 2; ++_i) \
;         __builtin_amdgcn_global_load_lds((const unsigned*)((const char*)(gbase) + (voff)[_i]), (PG8_LAS unsigned*)(lds + (bufoff) + ldsw + _i * 8192), 16, 0, 0); } while (0)
; #define PG8_LDA(dst, b, h) do { _Pragma("unroll") for (int m = 0; m < 4; ++m) _Pragma("unroll") for (int k = 0; k < 2; ++k) dst[m][k] = *(const PG8_LAS bf16x8*)(lds + PG8_SA(b, h) + aoff + m * 2048 + k * 1024); } while (0)
; #define PG8_LDB(dst, b, h) do { _Pragma("unroll") for (int n = 0; n < 2; ++n) _Pragma("unroll") for (int k = 0; k < 2; ++k) dst[n][k] = *(const PG8_LAS bf16x8*)(lds + PG8_SB(b, h) + boff + n * 2048 + k * 1024); } while (0)
; #define PG8_MMA(ai, bj, At, Bt) do { __builtin_amdgcn_s_setprio(1); _Pragma("unroll") for (int m = 0; m < 4; ++m) _Pragma("unroll") for (int n = 0; n < 2; ++n) _Pragma("unroll") for (int k = 0; k < 2; ++k) \
;         acc[ai][bj][m][n] = __builtin_amdgcn_mfma_f32_16x16x32_bf16(Bt[n][k], At[m][k], acc[ai][bj][m][n], 0, 0, 0); __builtin_amdgcn_s_setprio(0); } while (0)
; #define PG8_WAIT_V(n) asm volatile("s_waitcnt vmcnt(" #n ")" ::: "memory")
; #define PG8_WAIT_L(n) asm volatile("s_waitcnt lgkmcnt(" #n ")" ::: "memory")
; #define PG8_BAR __builtin_amdgcn_s_barrier()
; #define PG8_SCHED __builtin_amdgcn_sched_barrier(0)
; template <class Epi, class Sched, bool ALIGN_EPI = true>
; __device__ __forceinline__ void gemm_phase(PG8_LAS unsigned char* lds, const Gemm g, const Sched& S, const Epi& E, const int tid) {
;     ...
;             PG8_LDB(B0, 1, 0); PG8_LDB(B1, 1, 1); PG8_SCHED; PG8_LDA(At, 1, 0); PG8_STAGE(PG8_SA(0, 1), a2 + hstepA, voffA);
;             PG8_WAIT_V(8); PG8_WAIT_L(0); PG8_BAR; PG8_MMA(0, 0, At, B0); PG8_MMA(0, 1, At, B1); PG8_BAR; PG8_SCHED;
;             PG8_LDA(At, 1, 1); PG8_STAGE(PG8_SB(1, 0), b3, voffB); PG8_STAGE(PG8_SB(1, 1), b3 + hstepB, voffB); PG8_STAGE(PG8_SA(1, 0), a3, voffA);
;             PG8_WAIT_V(8); PG8_WAIT_L(0); PG8_BAR; PG8_MMA(1, 0, At, B0); PG8_MMA(1, 1, At, B1); PG8_BAR; PG8_SCHED;
;         }
	s_add_i32 s15, 0, 0x18000
	s_add_i32 s16, 0, 0x1c000
	v_add_u32_e32 v88, s15, v193
	v_add_u32_e32 v104, s16, v193
	ds_read_b128 v[72:75], v88
	ds_read_b128 v[76:79], v88 offset:1024
	ds_read_b128 v[84:87], v88 offset:2048
	ds_read_b128 v[88:91], v88 offset:3072
	ds_read_b128 v[92:95], v104
	ds_read_b128 v[96:99], v104 offset:1024
	ds_read_b128 v[100:103], v104 offset:2048
	ds_read_b128 v[104:107], v104 offset:3072
	s_add_u32 s78, s78, 0x80000
	s_addc_u32 s79, s79, 0
	s_mov_b32 m0, s88
	ds_read_b128 v[164:167], v200 offset:32768
	ds_read_b128 v[168:171], v200 offset:33792
	ds_read_b128 v[172:175], v200 offset:34816
	ds_read_b128 v[176:179], v200 offset:35840
	ds_read_b128 v[202:205], v200 offset:36864
	ds_read_b128 v[210:213], v200 offset:37888
	ds_read_b128 v[214:217], v200 offset:38912
	ds_read_b128 v[218:221], v200 offset:39936
	global_load_lds_dwordx4 v180, s[78:79]
	s_mov_b32 m0, s89
	s_nop 0
	global_load_lds_dwordx4 v182, s[78:79]
	s_waitcnt vmcnt(8)
	s_waitcnt lgkmcnt(0)
	s_barrier
	s_waitcnt lgkmcnt(0)
	v_mfma_f32_16x16x32_bf16 v[160:163], v[72:75], v[164:167], v[160:163]
	v_mfma_f32_16x16x32_bf16 v[160:163], v[76:79], v[168:171], v[160:163]
	v_mfma_f32_16x16x32_bf16 v[156:159], v[84:87], v[164:167], v[156:159]
	v_mfma_f32_16x16x32_bf16 v[156:159], v[88:91], v[168:171], v[156:159]
	v_mfma_f32_16x16x32_bf16 v[144:147], v[72:75], v[172:175], v[144:147]
	v_mfma_f32_16x16x32_bf16 v[144:147], v[76:79], v[176:179], v[144:147]
	v_mfma_f32_16x16x32_bf16 v[140:143], v[84:87], v[172:175], v[140:143]
	v_mfma_f32_16x16x32_bf16 v[140:143], v[88:91], v[176:179], v[140:143]
	v_mfma_f32_16x16x32_bf16 v[128:131], v[72:75], v[202:205], v[128:131]
	v_mfma_f32_16x16x32_bf16 v[128:131], v[76:79], v[210:213], v[128:131]
	v_mfma_f32_16x16x32_bf16 v[124:127], v[84:87], v[202:205], v[124:127]
	v_mfma_f32_16x16x32_bf16 v[124:127], v[88:91], v[210:213], v[124:127]
	v_mfma_f32_16x16x32_bf16 v[80:83], v[72:75], v[214:217], v[80:83]
	v_mfma_f32_16x16x32_bf16 v[80:83], v[76:79], v[218:221], v[80:83]
	v_mfma_f32_16x16x32_bf16 v[68:71], v[84:87], v[214:217], v[68:71]
	v_mfma_f32_16x16x32_bf16 v[68:71], v[88:91], v[218:221], v[68:71]
	v_mfma_f32_16x16x32_bf16 v[152:155], v[92:95], v[164:167], v[152:155]
	v_mfma_f32_16x16x32_bf16 v[152:155], v[96:99], v[168:171], v[152:155]
	v_mfma_f32_16x16x32_bf16 v[148:151], v[100:103], v[164:167], v[148:151]
	v_mfma_f32_16x16x32_bf16 v[148:151], v[104:107], v[168:171], v[148:151]
	v_mfma_f32_16x16x32_bf16 v[136:139], v[92:95], v[172:175], v[136:139]
	v_mfma_f32_16x16x32_bf16 v[136:139], v[96:99], v[176:179], v[136:139]
	v_mfma_f32_16x16x32_bf16 v[132:135], v[100:103], v[172:175], v[132:135]
	v_mfma_f32_16x16x32_bf16 v[132:135], v[104:107], v[176:179], v[132:135]
	v_mfma_f32_16x16x32_bf16 v[120:123], v[92:95], v[202:205], v[120:123]
	v_mfma_f32_16x16x32_bf16 v[120:123], v[96:99], v[210:213], v[120:123]
	v_mfma_f32_16x16x32_bf16 v[116:119], v[100:103], v[202:205], v[116:119]
	v_mfma_f32_16x16x32_bf16 v[116:119], v[104:107], v[210:213], v[116:119]
	v_mfma_f32_16x16x32_bf16 v[112:115], v[92:95], v[214:217], v[112:115]
	v_mfma_f32_16x16x32_bf16 v[112:115], v[96:99], v[218:221], v[112:115]
	v_mfma_f32_16x16x32_bf16 v[108:111], v[100:103], v[214:217], v[108:111]
	v_mfma_f32_16x16x32_bf16 v[108:111], v[104:107], v[218:221], v[108:111]
	s_barrier
	s_add_i32 s15, s15, s85
	s_add_u32 s96, s76, s36
	s_addc_u32 s97, s77, s37
	s_mov_b32 m0, s15
	ds_read_b128 v[164:167], v200 offset:49152
	ds_read_b128 v[168:171], v200 offset:50176
	ds_read_b128 v[172:175], v200 offset:51200
	ds_read_b128 v[176:179], v200 offset:52224
	ds_read_b128 v[202:205], v200 offset:53248
	ds_read_b128 v[210:213], v200 offset:54272
	ds_read_b128 v[214:217], v200 offset:55296
	ds_read_b128 v[218:221], v200 offset:56320
	global_load_lds_dwordx4 v2, s[96:97]
	s_add_i32 m0, s15, 0x2000
	s_add_u32 s76, s76, 0x80080
	s_addc_u32 s77, s77, 0
	s_add_i32 s15, s16, s85
	global_load_lds_dwordx4 v184, s[96:97]
	s_mov_b32 m0, s15
	s_nop 0
	global_load_lds_dwordx4 v2, s[76:77]
	s_add_i32 m0, s15, 0x2000
	s_nop 0
	global_load_lds_dwordx4 v184, s[76:77]
	s_add_u32 s96, s78, 0xfff80080
	s_addc_u32 s97, s79, -1
	s_mov_b32 m0, s92
	s_nop 0
	global_load_lds_dwordx4 v180, s[96:97]
	s_mov_b32 m0, s93
	s_nop 0
	global_load_lds_dwordx4 v182, s[96:97]
	s_waitcnt vmcnt(8)
	s_waitcnt lgkmcnt(0)
	s_barrier
	s_waitcnt lgkmcnt(0)
	v_mfma_f32_16x16x32_bf16 v[64:67], v[72:75], v[164:167], v[64:67]
	v_mfma_f32_16x16x32_bf16 v[64:67], v[76:79], v[168:171], v[64:67]
	v_mfma_f32_16x16x32_bf16 v[60:63], v[84:87], v[164:167], v[60:63]
	v_mfma_f32_16x16x32_bf16 v[60:63], v[88:91], v[168:171], v[60:63]
	v_mfma_f32_16x16x32_bf16 v[48:51], v[72:75], v[172:175], v[48:51]
	v_mfma_f32_16x16x32_bf16 v[48:51], v[76:79], v[176:179], v[48:51]
	v_mfma_f32_16x16x32_bf16 v[44:47], v[84:87], v[172:175], v[44:47]
	v_mfma_f32_16x16x32_bf16 v[44:47], v[88:91], v[176:179], v[44:47]
	v_mfma_f32_16x16x32_bf16 v[32:35], v[72:75], v[202:205], v[32:35]
	v_mfma_f32_16x16x32_bf16 v[32:35], v[76:79], v[210:213], v[32:35]
	v_mfma_f32_16x16x32_bf16 v[28:31], v[84:87], v[202:205], v[28:31]
	v_mfma_f32_16x16x32_bf16 v[28:31], v[88:91], v[210:213], v[28:31]
	v_mfma_f32_16x16x32_bf16 v[8:11], v[72:75], v[214:217], v[8:11]
	v_mfma_f32_16x16x32_bf16 v[8:11], v[76:79], v[218:221], v[8:11]
	v_mfma_f32_16x16x32_bf16 v[4:7], v[84:87], v[214:217], v[4:7]
	v_mfma_f32_16x16x32_bf16 v[4:7], v[88:91], v[218:221], v[4:7]
	v_mfma_f32_16x16x32_bf16 v[56:59], v[92:95], v[164:167], v[56:59]
	v_mfma_f32_16x16x32_bf16 v[56:59], v[96:99], v[168:171], v[56:59]
	v_mfma_f32_16x16x32_bf16 v[52:55], v[100:103], v[164:167], v[52:55]
	v_mfma_f32_16x16x32_bf16 v[52:55], v[104:107], v[168:171], v[52:55]
	v_mfma_f32_16x16x32_bf16 v[40:43], v[92:95], v[172:175], v[40:43]
	v_mfma_f32_16x16x32_bf16 v[40:43], v[96:99], v[176:179], v[40:43]
	v_mfma_f32_16x16x32_bf16 v[36:39], v[100:103], v[172:175], v[36:39]
	v_mfma_f32_16x16x32_bf16 v[36:39], v[104:107], v[176:179], v[36:39]
	v_mfma_f32_16x16x32_bf16 v[24:27], v[92:95], v[202:205], v[24:27]
	v_mfma_f32_16x16x32_bf16 v[24:27], v[96:99], v[210:213], v[24:27]
	v_mfma_f32_16x16x32_bf16 v[20:23], v[100:103], v[202:205], v[20:23]
	v_mfma_f32_16x16x32_bf16 v[20:23], v[104:107], v[210:213], v[20:23]
	v_mfma_f32_16x16x32_bf16 v[16:19], v[92:95], v[214:217], v[16:19]
	v_mfma_f32_16x16x32_bf16 v[16:19], v[96:99], v[218:221], v[16:19]
	v_mfma_f32_16x16x32_bf16 v[12:15], v[100:103], v[214:217], v[12:15]
	v_mfma_f32_16x16x32_bf16 v[12:15], v[104:107], v[218:221], v[12:15]
	s_barrier
	s_add_i32 s21, s21, 2
	s_add_u32 s74, s74, 0x100
	s_addc_u32 s75, s75, 0
	s_add_u32 s19, s19, 0x100
	s_addc_u32 s20, s20, 0
	s_cmp_gt_u32 s21, 29
	s_cbranch_scc0 .LBB0_1238
	s_and_b64 vcc, exec, s[56:57]
	s_cbranch_vccnz .LBB0_1264
	s_and_saveexec_b64 s[18:19], s[38:39]
	s_cbranch_execnz .LBB0_1265
